# RG-LRU gate math: canonicalising v_max x,x before v_max 0,x folded into one v_max (13 VALU per iteration off the critical RG instruction stream)
# baseline (speedup 1.0000x reference)
; __device__ __forceinline__ float bf2f(bf16_t v) { return __uint_as_float(((unsigned)v) << 16); }
; __device__ __forceinline__ float sigmoidf_(float x) { return __builtin_amdgcn_rcpf(1.f + __expf(-x)); }
; #define MFMA16(a, b, c) __builtin_amdgcn_mfma_f32_16x16x32_bf16((a), (b), (c), 0, 0, 0)
; __device__ __forceinline__ void rglru_unit(const Params& p, const WS& ws, int j, int u, bool dry = false) {
;     ...
;       for (int ks = 0; ks < 4; ++ks) {
;         const bf16x8 xf = *(const bf16x8*)(XC + (16 * w + lr) * 136 + 32 * ks + 8 * lq);
; #pragma unroll
;         for (int gate = 0; gate < 2; ++gate)
; #pragma unroll
;           for (int mt = 0; mt < 2; ++mt) {
;             const bf16x8 wf = *(const bf16x8*)(WG + (gate * 32 + 16 * mt + lr) * 136 + 32 * ks + 8 * lq);
;             ga_[gate][mt] = MFMA16(wf, xf, ga_[gate][mt]);
;           }
;       }
;       const int tok = 16 * w + lr;
; #pragma unroll
;       for (int mt = 0; mt < 2; ++mt)
; #pragma unroll
;         for (int jj = 0; jj < 4; ++jj) {
;           const int n = 16 * mt + 4 * lq + jj;
;           const float xcv = bf2f(XC[tok * 136 + 32 * jq + n]);
;           const float r = sigmoidf_(ga_[0][mt][jj] + ba[mt][jj]);
;           const float ig = sigmoidf_(ga_[1][mt][jj] + bx[mt][jj]);
;           const float la = -r * sp[mt][jj];
;           const float a = __expf(la);
;           const float x2 = 2.f * la;
;           const float om = x2 > -0.02f ? -x2 * (1.f + 0.5f * x2 * (1.f + x2 * (1.f / 3.f))) : 1.f - a * a;
;           const float mult = __builtin_amdgcn_sqrtf(fmaxf(om, 0.f));
;           AUa[tok * 33 + n] = a;
;           AUu[tok * 33 + n] = mult * ig * xcv;
;         }
.LBB0_1420:
	ds_read_b128 v[52:55], v111
	ds_read_b128 v[56:59], v112 offset:17408
	ds_read_b128 v[60:63], v112 offset:21760
	ds_read_b128 v[64:67], v112 offset:26112
	ds_read_b128 v[136:139], v112 offset:30464
	ds_read_b128 v[212:215], v111 offset:64
	ds_read_b128 v[216:219], v111 offset:128
	ds_read_b128 v[220:223], v111 offset:192
	ds_read_b128 v[224:227], v112 offset:17472
	ds_read_b128 v[228:231], v112 offset:21824
	ds_read_b128 v[232:235], v112 offset:26176
	ds_read_b128 v[244:247], v112 offset:30528
	ds_read_b128 v[248:251], v112 offset:17536
	ds_read_b128 v[252:255], v112 offset:21888
	s_waitcnt lgkmcnt(12)
	v_mfma_f32_16x16x32_bf16 v[56:59], v[56:59], v[52:55], 0
	s_waitcnt lgkmcnt(11)
	v_mfma_f32_16x16x32_bf16 v[60:63], v[60:63], v[52:55], 0
	s_waitcnt lgkmcnt(10)
	v_mfma_f32_16x16x32_bf16 v[64:67], v[64:67], v[52:55], 0
	s_waitcnt lgkmcnt(9)
	v_mfma_f32_16x16x32_bf16 v[52:55], v[136:139], v[52:55], 0
	s_nop 0
	s_nop 0
	s_waitcnt lgkmcnt(5)
	v_mfma_f32_16x16x32_bf16 v[56:59], v[224:227], v[212:215], v[56:59]
	ds_read_b128 v[224:227], v112 offset:26240
	s_nop 0
	s_waitcnt lgkmcnt(5)
	v_mfma_f32_16x16x32_bf16 v[60:63], v[228:231], v[212:215], v[60:63]
	ds_read_b128 v[228:231], v112 offset:30592
	s_nop 0
	s_waitcnt lgkmcnt(5)
	v_mfma_f32_16x16x32_bf16 v[64:67], v[232:235], v[212:215], v[64:67]
	ds_read_b128 v[232:235], v112 offset:17600
	s_nop 0
	s_waitcnt lgkmcnt(5)
	v_mfma_f32_16x16x32_bf16 v[52:55], v[244:247], v[212:215], v[52:55]
	ds_read_b128 v[244:247], v112 offset:21952
	s_nop 0
	s_nop 0
	s_waitcnt lgkmcnt(5)
	v_mfma_f32_16x16x32_bf16 v[56:59], v[248:251], v[216:219], v[56:59]
	ds_read_b128 v[248:251], v112 offset:26304
	s_nop 0
	s_waitcnt lgkmcnt(5)
	v_mfma_f32_16x16x32_bf16 v[60:63], v[252:255], v[216:219], v[60:63]
	ds_read_b128 v[252:255], v112 offset:30656
	s_nop 0
	s_waitcnt lgkmcnt(5)
	v_mfma_f32_16x16x32_bf16 v[140:143], v[224:227], v[216:219], v[64:67]
	s_nop 2
	s_nop 0
	s_waitcnt lgkmcnt(4)
	v_mfma_f32_16x16x32_bf16 v[52:55], v[228:231], v[216:219], v[52:55]
	s_nop 0
	s_nop 0
	ds_read_u16 v13, v113
	s_waitcnt lgkmcnt(4)
	v_mfma_f32_16x16x32_bf16 v[64:67], v[232:235], v[220:223], v[56:59]
	s_nop 2
	s_nop 0
	s_waitcnt lgkmcnt(3)
	v_mfma_f32_16x16x32_bf16 v[56:59], v[244:247], v[220:223], v[60:63]
	s_nop 2
	s_nop 0
	v_add_f32_e32 v14, v0, v64
	v_mul_f32_e32 v14, 0xbfb8aa3b, v14
	v_exp_f32_e32 v14, v14
	s_waitcnt lgkmcnt(2)
	v_mfma_f32_16x16x32_bf16 v[60:63], v[248:251], v[220:223], v[140:143]
	s_nop 2
	s_nop 0
	v_add_f32_e32 v14, 1.0, v14
	v_rcp_f32_e64 v14, -v14
	s_waitcnt lgkmcnt(0)
	v_mfma_f32_16x16x32_bf16 v[52:55], v[252:255], v[220:223], v[52:55]
	v_mul_f32_e32 v14, v89, v14
	v_mul_f32_e32 v15, 0x3fb8aa3b, v14
	v_exp_f32_e32 v15, v15
	v_add_f32_e32 v14, v14, v14
	v_cmp_nlt_f32_e64 s[52:53], s29, v14
	s_and_saveexec_b64 s[4:5], s[52:53]
	s_xor_b64 s[4:5], exec, s[4:5]
	v_fma_f32 v64, -v15, v15, 1.0
	s_andn2_saveexec_b64 s[4:5], s[4:5]
	v_pk_mul_f32 v[136:137], v[14:15], s[88:89] op_sel_hi:[0,1]
	v_add_f32_e32 v64, 1.0, v137
	v_fma_f32 v64, v136, v64, 1.0
	v_mul_f32_e64 v64, v64, -v14
	s_or_b64 exec, exec, s[4:5]
	v_add_f32_e32 v14, v8, v60
	v_max_f32_e32 v60, v64, v64
	v_add_f32_e32 v64, v1, v65
	v_mul_f32_e32 v14, 0xbfb8aa3b, v14
	v_mul_f32_e32 v64, 0xbfb8aa3b, v64
	v_exp_f32_e32 v14, v14
	v_exp_f32_e32 v64, v64
	v_max_f32_e32 v60, 0, v60
	v_sqrt_f32_e32 v60, v60
	v_add_f32_e32 v14, 1.0, v14
	v_add_f32_e32 v64, 1.0, v64
	v_rcp_f32_e32 v14, v14
	v_rcp_f32_e64 v64, -v64
	v_lshlrev_b32_e32 v13, 16, v13
	v_mul_f32_e32 v14, v14, v60
	v_mul_f32_e32 v64, v93, v64
	v_mul_f32_e32 v14, v14, v13
	ds_read_u16 v60, v113 offset:2
	v_mul_f32_e32 v13, 0x3fb8aa3b, v64
	v_exp_f32_e32 v13, v13
	ds_write2st64_b32 v72, v15, v14 offset0:136 offset1:169
	v_add_f32_e32 v14, v64, v64
	v_cmp_nlt_f32_e64 s[52:53], s29, v14
	s_and_saveexec_b64 s[4:5], s[52:53]
	s_xor_b64 s[4:5], exec, s[4:5]
	v_fma_f32 v15, -v13, v13, 1.0
	s_andn2_saveexec_b64 s[4:5], s[4:5]
	v_pk_mul_f32 v[64:65], v[14:15], s[88:89] op_sel_hi:[0,1]
	v_add_f32_e32 v15, 1.0, v65
	v_fma_f32 v15, v64, v15, 1.0
	v_mul_f32_e64 v15, v15, -v14
	s_or_b64 exec, exec, s[4:5]
	s_waitcnt lgkmcnt(1)
	v_lshlrev_b32_e32 v14, 16, v60
	v_add_f32_e32 v60, v9, v61
	v_mul_f32_e32 v60, 0xbfb8aa3b, v60
	v_exp_f32_e32 v60, v60
	v_max_f32_e32 v15, 0, v15
	v_sqrt_f32_e32 v15, v15
	v_add_f32_e32 v60, 1.0, v60
	v_rcp_f32_e32 v60, v60
	v_add_u32_e32 v135, 4, v72
	v_mul_f32_e32 v15, v60, v15
	v_mul_f32_e32 v14, v15, v14
	ds_write2st64_b32 v135, v13, v14 offset0:136 offset1:169
	v_add_f32_e32 v14, v2, v66
	v_mul_f32_e32 v14, 0xbfb8aa3b, v14
	v_exp_f32_e32 v14, v14
	ds_read_u16 v13, v113 offset:4
	v_add_f32_e32 v14, 1.0, v14
	v_rcp_f32_e64 v14, -v14
	s_nop 0
	v_mul_f32_e32 v14, v95, v14
	v_mul_f32_e32 v15, 0x3fb8aa3b, v14
	v_exp_f32_e32 v15, v15
	v_add_f32_e32 v14, v14, v14
	v_cmp_nlt_f32_e64 s[52:53], s29, v14
	s_and_saveexec_b64 s[4:5], s[52:53]
	s_xor_b64 s[4:5], exec, s[4:5]
	v_fma_f32 v60, -v15, v15, 1.0
	s_andn2_saveexec_b64 s[4:5], s[4:5]
	v_pk_mul_f32 v[60:61], v[14:15], s[88:89] op_sel_hi:[0,1]
	v_add_f32_e32 v61, 1.0, v61
	v_fma_f32 v60, v60, v61, 1.0
	v_mul_f32_e64 v60, v60, -v14
	s_or_b64 exec, exec, s[4:5]
	v_add_f32_e32 v14, v10, v62
	v_mul_f32_e32 v14, 0xbfb8aa3b, v14
	v_exp_f32_e32 v14, v14
	v_max_f32_e32 v60, 0, v60
	v_sqrt_f32_e32 v60, v60
	v_add_f32_e32 v14, 1.0, v14
	v_rcp_f32_e32 v14, v14
	s_waitcnt lgkmcnt(0)
; __device__ __forceinline__ float bf2f(bf16_t v) { return __uint_as_float(((unsigned)v) << 16); }
; __device__ __forceinline__ float sigmoidf_(float x) { return __builtin_amdgcn_rcpf(1.f + __expf(-x)); }
; __device__ __forceinline__ void rglru_unit(const Params& p, const WS& ws, int j, int u, bool dry = false) {
;     ...
; #pragma unroll
;       for (int mt = 0; mt < 2; ++mt)
; #pragma unroll
;         for (int jj = 0; jj < 4; ++jj) {
;           const int n = 16 * mt + 4 * lq + jj;
;           const float xcv = bf2f(XC[tok * 136 + 32 * jq + n]);
;           const float r = sigmoidf_(ga_[0][mt][jj] + ba[mt][jj]);
;           const float ig = sigmoidf_(ga_[1][mt][jj] + bx[mt][jj]);
;           const float la = -r * sp[mt][jj];
;           const float a = __expf(la);
;           const float x2 = 2.f * la;
;           const float om = x2 > -0.02f ? -x2 * (1.f + 0.5f * x2 * (1.f + x2 * (1.f / 3.f))) : 1.f - a * a;
;           const float mult = __builtin_amdgcn_sqrtf(fmaxf(om, 0.f));
;           AUa[tok * 33 + n] = a;
;           AUu[tok * 33 + n] = mult * ig * xcv;
;         }
;     }
;     __syncthreads();
;     {
;       float A = 1.f, Hh = 0.f;
; #pragma unroll
;       for (int i = 0; i < 8; ++i) {
;         const float a = AUa[(8 * ssg + i) * 33 + sc], uu = AUu[(8 * ssg + i) * 33 + sc];
;         Hh = a * Hh + uu; A *= a;
;       }
;       SEGA[ssg * 32 + sc] = A; SEGH[ssg * 32 + sc] = Hh;
;     }
;     __syncthreads();
;     float hin = CARRY[sc];
; #pragma unroll
;     for (int s2 = 0; s2 < 7; ++s2)
;       if (s2 < ssg) hin = SEGA[s2 * 32 + sc] * hin + SEGH[s2 * 32 + sc];
	v_lshlrev_b32_e32 v13, 16, v13
	v_add_u32_e32 v136, 8, v72
	v_mul_f32_e32 v14, v14, v60
	v_mul_f32_e32 v13, v14, v13
	v_add_f32_e32 v14, v3, v67
	v_mul_f32_e32 v14, 0xbfb8aa3b, v14
	v_exp_f32_e32 v14, v14
	ds_write2st64_b32 v136, v15, v13 offset0:136 offset1:169
	ds_read_u16 v13, v113 offset:6
	v_add_f32_e32 v14, 1.0, v14
	v_rcp_f32_e64 v14, -v14
	s_nop 0
	v_mul_f32_e32 v14, v96, v14
	v_mul_f32_e32 v15, 0x3fb8aa3b, v14
	v_exp_f32_e32 v15, v15
	v_add_f32_e32 v14, v14, v14
	v_cmp_nlt_f32_e64 s[52:53], s29, v14
	s_and_saveexec_b64 s[4:5], s[52:53]
	s_xor_b64 s[4:5], exec, s[4:5]
	v_fma_f32 v60, -v15, v15, 1.0
	s_andn2_saveexec_b64 s[4:5], s[4:5]
	v_pk_mul_f32 v[60:61], v[14:15], s[88:89] op_sel_hi:[0,1]
	v_add_f32_e32 v61, 1.0, v61
	v_fma_f32 v60, v60, v61, 1.0
	v_mul_f32_e64 v60, v60, -v14
	s_or_b64 exec, exec, s[4:5]
	v_add_f32_e32 v14, v11, v63
	v_mul_f32_e32 v14, 0xbfb8aa3b, v14
	v_exp_f32_e32 v14, v14
	v_max_f32_e32 v60, 0, v60
	v_sqrt_f32_e32 v60, v60
	v_add_f32_e32 v14, 1.0, v14
	v_rcp_f32_e32 v14, v14
	s_waitcnt lgkmcnt(0)
	v_lshlrev_b32_e32 v13, 16, v13
	v_add_u32_e32 v139, 12, v72
	v_mul_f32_e32 v14, v14, v60
	v_mul_f32_e32 v13, v14, v13
	v_add_f32_e32 v14, v4, v56
	v_mul_f32_e32 v14, 0xbfb8aa3b, v14
	v_exp_f32_e32 v14, v14
	ds_write2st64_b32 v139, v15, v13 offset0:136 offset1:169
	ds_read_u16 v13, v113 offset:32
	v_add_f32_e32 v14, 1.0, v14
	v_rcp_f32_e64 v14, -v14
	s_nop 0
	v_mul_f32_e32 v14, v97, v14
	v_mul_f32_e32 v15, 0x3fb8aa3b, v14
	v_exp_f32_e32 v15, v15
	v_add_f32_e32 v14, v14, v14
	v_cmp_nlt_f32_e64 s[52:53], s29, v14
	s_and_saveexec_b64 s[4:5], s[52:53]
	s_xor_b64 s[4:5], exec, s[4:5]
	v_fma_f32 v56, -v15, v15, 1.0
	s_andn2_saveexec_b64 s[4:5], s[4:5]
	v_pk_mul_f32 v[60:61], v[14:15], s[88:89] op_sel_hi:[0,1]
	v_add_f32_e32 v56, 1.0, v61
	v_fma_f32 v56, v60, v56, 1.0
	v_mul_f32_e64 v56, v56, -v14
	s_or_b64 exec, exec, s[4:5]
	v_add_f32_e32 v14, v16, v52
	v_mul_f32_e32 v14, 0xbfb8aa3b, v14
	v_exp_f32_e32 v14, v14
	v_max_f32_e32 v52, 0, v56
	v_sqrt_f32_e32 v52, v52
	v_add_f32_e32 v14, 1.0, v14
	v_rcp_f32_e32 v14, v14
	s_waitcnt lgkmcnt(0)
	v_lshlrev_b32_e32 v13, 16, v13
	v_add_u32_e32 v141, 64, v72
	v_mul_f32_e32 v14, v14, v52
	v_mul_f32_e32 v13, v14, v13
	v_add_f32_e32 v14, v5, v57
	v_mul_f32_e32 v14, 0xbfb8aa3b, v14
	v_exp_f32_e32 v14, v14
	ds_write2st64_b32 v141, v15, v13 offset0:136 offset1:169
	ds_read_u16 v13, v113 offset:34
	v_add_f32_e32 v14, 1.0, v14
	v_rcp_f32_e64 v14, -v14
	s_nop 0
	v_mul_f32_e32 v14, v98, v14
	v_mul_f32_e32 v15, 0x3fb8aa3b, v14
	v_exp_f32_e32 v15, v15
	v_add_f32_e32 v14, v14, v14
	v_cmp_nlt_f32_e64 s[52:53], s29, v14
	s_and_saveexec_b64 s[4:5], s[52:53]
	s_xor_b64 s[4:5], exec, s[4:5]
	v_fma_f32 v52, -v15, v15, 1.0
	s_andn2_saveexec_b64 s[4:5], s[4:5]
	v_pk_mul_f32 v[56:57], v[14:15], s[88:89] op_sel_hi:[0,1]
	v_add_f32_e32 v52, 1.0, v57
	v_fma_f32 v52, v56, v52, 1.0
	v_mul_f32_e64 v52, v52, -v14
	s_or_b64 exec, exec, s[4:5]
	v_add_f32_e32 v14, v17, v53
	v_mul_f32_e32 v14, 0xbfb8aa3b, v14
	v_exp_f32_e32 v14, v14
	v_max_f32_e32 v52, 0, v52
	v_sqrt_f32_e32 v52, v52
	v_add_f32_e32 v14, 1.0, v14
	v_rcp_f32_e32 v14, v14
	s_waitcnt lgkmcnt(0)
	v_lshlrev_b32_e32 v13, 16, v13
	v_add_u32_e32 v142, 0x44, v72
	v_mul_f32_e32 v14, v14, v52
	v_mul_f32_e32 v13, v14, v13
	v_add_f32_e32 v14, v6, v58
	v_mul_f32_e32 v14, 0xbfb8aa3b, v14
	v_exp_f32_e32 v14, v14
	ds_write2st64_b32 v142, v15, v13 offset0:136 offset1:169
	ds_read_u16 v13, v113 offset:36
	v_add_f32_e32 v14, 1.0, v14
	v_rcp_f32_e64 v14, -v14
	s_nop 0
	v_mul_f32_e32 v14, v99, v14
	v_mul_f32_e32 v15, 0x3fb8aa3b, v14
	v_exp_f32_e32 v15, v15
	v_add_f32_e32 v14, v14, v14
	v_cmp_nlt_f32_e64 s[52:53], s29, v14
	s_and_saveexec_b64 s[4:5], s[52:53]
	s_xor_b64 s[4:5], exec, s[4:5]
	v_fma_f32 v52, -v15, v15, 1.0
	s_andn2_saveexec_b64 s[4:5], s[4:5]
	v_pk_mul_f32 v[52:53], v[14:15], s[88:89] op_sel_hi:[0,1]
	v_add_f32_e32 v53, 1.0, v53
	v_fma_f32 v52, v52, v53, 1.0
	v_mul_f32_e64 v52, v52, -v14
	s_or_b64 exec, exec, s[4:5]
	v_add_f32_e32 v14, v18, v54
	v_mul_f32_e32 v14, 0xbfb8aa3b, v14
	v_exp_f32_e32 v14, v14
	v_max_f32_e32 v52, 0, v52
	v_sqrt_f32_e32 v52, v52
	v_add_f32_e32 v14, 1.0, v14
	v_rcp_f32_e32 v14, v14
	s_waitcnt lgkmcnt(0)
	v_lshlrev_b32_e32 v13, 16, v13
	v_add_u32_e32 v144, 0x48, v72
	v_mul_f32_e32 v14, v14, v52
	v_mul_f32_e32 v13, v14, v13
	v_add_f32_e32 v14, v7, v59
	v_mul_f32_e32 v14, 0xbfb8aa3b, v14
	v_exp_f32_e32 v14, v14
	ds_write2st64_b32 v144, v15, v13 offset0:136 offset1:169
	ds_read_u16 v13, v113 offset:38
	v_add_f32_e32 v14, 1.0, v14
	v_rcp_f32_e64 v14, -v14
	s_nop 0
	v_mul_f32_e32 v14, v105, v14
	v_mul_f32_e32 v15, 0x3fb8aa3b, v14
	v_exp_f32_e32 v15, v15
	v_add_f32_e32 v14, v14, v14
	v_cmp_nlt_f32_e64 s[52:53], s29, v14
	s_and_saveexec_b64 s[4:5], s[52:53]
	s_xor_b64 s[4:5], exec, s[4:5]
	v_fma_f32 v52, -v15, v15, 1.0
	s_andn2_saveexec_b64 s[4:5], s[4:5]
	v_pk_mul_f32 v[52:53], v[14:15], s[88:89] op_sel_hi:[0,1]
	v_add_f32_e32 v53, 1.0, v53
	v_fma_f32 v52, v52, v53, 1.0
	v_mul_f32_e64 v52, v52, -v14
	s_or_b64 exec, exec, s[4:5]
	v_add_f32_e32 v14, v19, v55
	v_mul_f32_e32 v14, 0xbfb8aa3b, v14
	v_exp_f32_e32 v14, v14
	v_max_f32_e32 v52, 0, v52
	v_sqrt_f32_e32 v52, v52
	v_add_f32_e32 v14, 1.0, v14
	v_rcp_f32_e32 v14, v14
	s_waitcnt lgkmcnt(0)
	v_lshlrev_b32_e32 v13, 16, v13
	v_add_u32_e32 v145, 0x4c, v72
	v_add_u32_e32 v137, 0x8800, v114
	v_mul_f32_e32 v14, v14, v52
	v_mul_f32_e32 v13, v14, v13
	v_add_u32_e32 v138, 0xa800, v114
	ds_write2st64_b32 v145, v15, v13 offset0:136 offset1:169
	s_waitcnt lgkmcnt(0)
	s_barrier
	ds_read2_b32 v[14:15], v137 offset1:33
	ds_read2_b32 v[52:53], v138 offset0:64 offset1:97
	v_add_u32_e32 v140, 0xac00, v114
	s_waitcnt lgkmcnt(0)
	v_fma_f32 v13, 0, v14, v52
	v_fmac_f32_e32 v53, v13, v15
	v_mul_f32_e32 v13, v14, v15
	ds_read2_b32 v[14:15], v137 offset0:66 offset1:99
	ds_read2_b32 v[54:55], v138 offset0:130 offset1:163
	s_waitcnt lgkmcnt(1)
	v_mul_f32_e32 v13, v13, v14
	s_waitcnt lgkmcnt(0)
	v_fma_f32 v52, v53, v14, v54
	v_fmac_f32_e32 v55, v52, v15
	v_mul_f32_e32 v13, v13, v15
	ds_read2_b32 v[14:15], v137 offset0:132 offset1:165
	ds_read2_b32 v[52:53], v138 offset0:196 offset1:229
	s_waitcnt lgkmcnt(1)
	v_mul_f32_e32 v13, v13, v14
	s_waitcnt lgkmcnt(0)
	v_fma_f32 v52, v55, v14, v52
	v_fmac_f32_e32 v53, v52, v15
	v_mul_f32_e32 v13, v13, v15
	ds_read2_b32 v[14:15], v137 offset0:198 offset1:231
	ds_read2_b32 v[54:55], v140 offset0:6 offset1:39
	s_waitcnt lgkmcnt(1)
	v_mul_f32_e32 v13, v13, v14
	s_waitcnt lgkmcnt(0)
	v_fma_f32 v52, v53, v14, v54
	v_fmac_f32_e32 v55, v52, v15
	v_mul_f32_e32 v13, v13, v15
	ds_write2st64_b32 v78, v13, v55 offset0:202 offset1:206
	s_waitcnt lgkmcnt(0)
	s_barrier
	ds_read_b32 v13, v115 offset:53760
	s_and_saveexec_b64 s[4:5], vcc
	s_cbranch_execz .LBB0_1548
	ds_read2st64_b32 v[14:15], v115 offset0:202 offset1:206
	s_waitcnt lgkmcnt(0)
	v_fmac_f32_e32 v15, v13, v14
	v_mov_b32_e32 v13, v15
	s_or_b64 exec, exec, s[4:5]
	v_add_u32_e32 v143, 0x80, v115
	s_and_saveexec_b64 s[4:5], s[38:39]
	s_cbranch_execnz .LBB0_1549

; __device__ __forceinline__ float bf2f(bf16_t v) { return __uint_as_float(((unsigned)v) << 16); }
; __device__ __forceinline__ float sigmoidf_(float x) { return __builtin_amdgcn_rcpf(1.f + __expf(-x)); }
; #define MFMA16(a, b, c) __builtin_amdgcn_mfma_f32_16x16x32_bf16((a), (b), (c), 0, 0, 0)
; __device__ __forceinline__ void rglru_unit(const Params& p, const WS& ws, int j, int u, bool dry = false) {
;     ...
;       for (int ks = 0; ks < 4; ++ks) {
;         const bf16x8 xf = *(const bf16x8*)(XC + (16 * w + lr) * 136 + 32 * ks + 8 * lq);
; #pragma unroll
;         for (int gate = 0; gate < 2; ++gate)
; #pragma unroll
;           for (int mt = 0; mt < 2; ++mt) {
;             const bf16x8 wf = *(const bf16x8*)(WG + (gate * 32 + 16 * mt + lr) * 136 + 32 * ks + 8 * lq);
;             ga_[gate][mt] = MFMA16(wf, xf, ga_[gate][mt]);
;           }
;       }
;       const int tok = 16 * w + lr;
; #pragma unroll
;       for (int mt = 0; mt < 2; ++mt)
; #pragma unroll
;         for (int jj = 0; jj < 4; ++jj) {
;           const int n = 16 * mt + 4 * lq + jj;
;           const float xcv = bf2f(XC[tok * 136 + 32 * jq + n]);
;           const float r = sigmoidf_(ga_[0][mt][jj] + ba[mt][jj]);
;           const float ig = sigmoidf_(ga_[1][mt][jj] + bx[mt][jj]);
;           const float la = -r * sp[mt][jj];
;           const float a = __expf(la);
;           const float x2 = 2.f * la;
;           const float om = x2 > -0.02f ? -x2 * (1.f + 0.5f * x2 * (1.f + x2 * (1.f / 3.f))) : 1.f - a * a;
;           const float mult = __builtin_amdgcn_sqrtf(fmaxf(om, 0.f));
;           AUa[tok * 33 + n] = a;
;           AUu[tok * 33 + n] = mult * ig * xcv;
;         }
.LBB0_1505:
	ds_read_b128 v[52:55], v111
	ds_read_b128 v[56:59], v112 offset:17408
	ds_read_b128 v[60:63], v112 offset:21760
	ds_read_b128 v[64:67], v112 offset:26112
	ds_read_b128 v[120:123], v112 offset:30464
	ds_read_b128 v[212:215], v111 offset:64
	ds_read_b128 v[216:219], v111 offset:128
	ds_read_b128 v[220:223], v111 offset:192
	ds_read_b128 v[224:227], v112 offset:17472
	ds_read_b128 v[228:231], v112 offset:21824
	ds_read_b128 v[232:235], v112 offset:26176
	ds_read_b128 v[244:247], v112 offset:30528
	ds_read_b128 v[248:251], v112 offset:17536
	ds_read_b128 v[252:255], v112 offset:21888
	s_waitcnt lgkmcnt(12)
	v_mfma_f32_16x16x32_bf16 v[56:59], v[56:59], v[52:55], 0
	s_waitcnt lgkmcnt(11)
	v_mfma_f32_16x16x32_bf16 v[60:63], v[60:63], v[52:55], 0
	s_waitcnt lgkmcnt(10)
	v_mfma_f32_16x16x32_bf16 v[64:67], v[64:67], v[52:55], 0
	s_waitcnt lgkmcnt(9)
	v_mfma_f32_16x16x32_bf16 v[52:55], v[120:123], v[52:55], 0
	s_nop 0
	s_nop 0
	s_waitcnt lgkmcnt(5)
	v_mfma_f32_16x16x32_bf16 v[56:59], v[224:227], v[212:215], v[56:59]
	ds_read_b128 v[224:227], v112 offset:26240
	s_nop 0
	s_waitcnt lgkmcnt(5)
	v_mfma_f32_16x16x32_bf16 v[60:63], v[228:231], v[212:215], v[60:63]
	ds_read_b128 v[228:231], v112 offset:30592
	s_nop 0
	s_waitcnt lgkmcnt(5)
	v_mfma_f32_16x16x32_bf16 v[64:67], v[232:235], v[212:215], v[64:67]
	ds_read_b128 v[232:235], v112 offset:17600
	s_nop 0
	s_waitcnt lgkmcnt(5)
	v_mfma_f32_16x16x32_bf16 v[52:55], v[244:247], v[212:215], v[52:55]
	ds_read_b128 v[244:247], v112 offset:21952
	s_nop 0
	s_nop 0
	s_waitcnt lgkmcnt(5)
	v_mfma_f32_16x16x32_bf16 v[56:59], v[248:251], v[216:219], v[56:59]
	ds_read_b128 v[248:251], v112 offset:26304
	s_nop 0
	s_waitcnt lgkmcnt(5)
	v_mfma_f32_16x16x32_bf16 v[60:63], v[252:255], v[216:219], v[60:63]
	ds_read_b128 v[252:255], v112 offset:30656
	s_nop 0
	s_waitcnt lgkmcnt(5)
	v_mfma_f32_16x16x32_bf16 v[154:157], v[224:227], v[216:219], v[64:67]
	s_nop 2
	s_nop 0
	s_waitcnt lgkmcnt(4)
	v_mfma_f32_16x16x32_bf16 v[52:55], v[228:231], v[216:219], v[52:55]
	s_nop 0
	s_nop 0
	ds_read_u16 v15, v113
	s_waitcnt lgkmcnt(4)
	v_mfma_f32_16x16x32_bf16 v[64:67], v[232:235], v[220:223], v[56:59]
	s_nop 2
	s_nop 0
	s_waitcnt lgkmcnt(3)
	v_mfma_f32_16x16x32_bf16 v[56:59], v[244:247], v[220:223], v[60:63]
	s_nop 2
	s_nop 0
	v_add_f32_e32 v14, v0, v64
	v_mul_f32_e32 v14, 0xbfb8aa3b, v14
	v_exp_f32_e32 v14, v14
	s_waitcnt lgkmcnt(2)
	v_mfma_f32_16x16x32_bf16 v[60:63], v[248:251], v[220:223], v[154:157]
	s_nop 2
	s_nop 0
	v_add_f32_e32 v14, 1.0, v14
	v_rcp_f32_e64 v14, -v14
	s_waitcnt lgkmcnt(0)
	v_mfma_f32_16x16x32_bf16 v[52:55], v[252:255], v[220:223], v[52:55]
	v_mul_f32_e32 v14, v89, v14
	v_mul_f32_e32 v64, 0x3fb8aa3b, v14
	v_exp_f32_e32 v64, v64
	v_add_f32_e32 v14, v14, v14
	v_cmp_nlt_f32_e64 s[52:53], s29, v14
	s_and_saveexec_b64 s[4:5], s[52:53]
	s_xor_b64 s[4:5], exec, s[4:5]
	v_fma_f32 v119, -v64, v64, 1.0
	s_andn2_saveexec_b64 s[4:5], s[4:5]
	v_pk_mul_f32 v[120:121], v[14:15], s[88:89] op_sel_hi:[0,1]
	v_add_f32_e32 v119, 1.0, v121
	v_fma_f32 v119, v120, v119, 1.0
	v_mul_f32_e64 v119, v119, -v14
	s_or_b64 exec, exec, s[4:5]
	v_add_f32_e32 v14, v8, v60
	v_add_f32_e32 v65, v1, v65
	v_mul_f32_e32 v14, 0xbfb8aa3b, v14
	v_mul_f32_e32 v65, 0xbfb8aa3b, v65
	v_exp_f32_e32 v14, v14
	v_exp_f32_e32 v65, v65
	v_max_f32_e32 v60, 0, v119
	v_add_f32_e32 v14, 1.0, v14
	v_add_f32_e32 v65, 1.0, v65
	v_rcp_f32_e32 v14, v14
	v_sqrt_f32_e32 v60, v60
	v_rcp_f32_e64 v65, -v65
	v_lshlrev_b32_e32 v15, 16, v15
	v_mul_f32_e32 v14, v14, v60
	v_mul_f32_e32 v65, v93, v65
	v_mul_f32_e32 v14, v14, v15
	ds_read_u16 v60, v113 offset:2
	v_mul_f32_e32 v15, 0x3fb8aa3b, v65
	v_exp_f32_e32 v15, v15
	ds_write2st64_b32 v72, v64, v14 offset0:136 offset1:169
	v_add_f32_e32 v14, v65, v65
	v_cmp_nlt_f32_e64 s[52:53], s29, v14
	s_and_saveexec_b64 s[4:5], s[52:53]
	s_xor_b64 s[4:5], exec, s[4:5]
	v_fma_f32 v64, -v15, v15, 1.0
	s_andn2_saveexec_b64 s[4:5], s[4:5]
	v_pk_mul_f32 v[64:65], v[14:15], s[88:89] op_sel_hi:[0,1]
	v_add_f32_e32 v65, 1.0, v65
	v_fma_f32 v64, v64, v65, 1.0
	v_mul_f32_e64 v64, v64, -v14
	s_or_b64 exec, exec, s[4:5]
	v_add_f32_e32 v14, v9, v61
	v_max_f32_e32 v61, v64, v64
	v_add_f32_e32 v64, v2, v66
	v_mul_f32_e32 v14, 0xbfb8aa3b, v14
	v_mul_f32_e32 v64, 0xbfb8aa3b, v64
	v_exp_f32_e32 v14, v14
	v_exp_f32_e32 v64, v64
	v_max_f32_e32 v61, 0, v61
	v_sqrt_f32_e32 v61, v61
	v_add_f32_e32 v14, 1.0, v14
	v_add_f32_e32 v64, 1.0, v64
	v_rcp_f32_e32 v14, v14
	v_rcp_f32_e64 v64, -v64
	s_waitcnt lgkmcnt(1)
	v_lshlrev_b32_e32 v60, 16, v60
	v_mul_f32_e32 v14, v14, v61
	v_mul_f32_e32 v64, v95, v64
	v_mul_f32_e32 v14, v14, v60
	ds_read_u16 v61, v113 offset:4
	v_mul_f32_e32 v60, 0x3fb8aa3b, v64
	v_exp_f32_e32 v60, v60
	ds_write2st64_b32 v135, v15, v14 offset0:136 offset1:169
	v_add_f32_e32 v14, v64, v64
	v_cmp_nlt_f32_e64 s[52:53], s29, v14
	s_and_saveexec_b64 s[4:5], s[52:53]
	s_xor_b64 s[4:5], exec, s[4:5]
	v_fma_f32 v15, -v60, v60, 1.0
	s_andn2_saveexec_b64 s[4:5], s[4:5]
	v_pk_mul_f32 v[64:65], v[14:15], s[88:89] op_sel_hi:[0,1]
	v_add_f32_e32 v15, 1.0, v65
	v_fma_f32 v15, v64, v15, 1.0
	v_mul_f32_e64 v15, v15, -v14
	s_or_b64 exec, exec, s[4:5]
	v_add_f32_e32 v14, v10, v62
	v_add_f32_e32 v62, v3, v67
	v_mul_f32_e32 v14, 0xbfb8aa3b, v14
	v_mul_f32_e32 v62, 0xbfb8aa3b, v62
	v_exp_f32_e32 v14, v14
	v_exp_f32_e32 v62, v62
	v_max_f32_e32 v15, 0, v15
	v_add_f32_e32 v14, 1.0, v14
	v_add_f32_e32 v62, 1.0, v62
	v_rcp_f32_e32 v14, v14
	v_sqrt_f32_e32 v15, v15
	v_rcp_f32_e64 v62, -v62
	s_waitcnt lgkmcnt(1)
; __device__ __forceinline__ float bf2f(bf16_t v) { return __uint_as_float(((unsigned)v) << 16); }
; __device__ __forceinline__ float sigmoidf_(float x) { return __builtin_amdgcn_rcpf(1.f + __expf(-x)); }
; __device__ __forceinline__ void rglru_unit(const Params& p, const WS& ws, int j, int u, bool dry = false) {
;     ...
; #pragma unroll
;       for (int mt = 0; mt < 2; ++mt)
; #pragma unroll
;         for (int jj = 0; jj < 4; ++jj) {
;           const int n = 16 * mt + 4 * lq + jj;
;           const float xcv = bf2f(XC[tok * 136 + 32 * jq + n]);
;           const float r = sigmoidf_(ga_[0][mt][jj] + ba[mt][jj]);
;           const float ig = sigmoidf_(ga_[1][mt][jj] + bx[mt][jj]);
;           const float la = -r * sp[mt][jj];
;           const float a = __expf(la);
;           const float x2 = 2.f * la;
;           const float om = x2 > -0.02f ? -x2 * (1.f + 0.5f * x2 * (1.f + x2 * (1.f / 3.f))) : 1.f - a * a;
;           const float mult = __builtin_amdgcn_sqrtf(fmaxf(om, 0.f));
;           AUa[tok * 33 + n] = a;
;           AUu[tok * 33 + n] = mult * ig * xcv;
;         }
;     }
;     __syncthreads();
;     {
;       float A = 1.f, Hh = 0.f;
; #pragma unroll
;       for (int i = 0; i < 8; ++i) {
;         const float a = AUa[(8 * ssg + i) * 33 + sc], uu = AUu[(8 * ssg + i) * 33 + sc];
;         Hh = a * Hh + uu; A *= a;
;       }
;       SEGA[ssg * 32 + sc] = A; SEGH[ssg * 32 + sc] = Hh;
;     }
;     __syncthreads();
;     float hin = CARRY[sc];
; #pragma unroll
;     for (int s2 = 0; s2 < 7; ++s2)
;       if (s2 < ssg) hin = SEGA[s2 * 32 + sc] * hin + SEGH[s2 * 32 + sc];
	v_lshlrev_b32_e32 v61, 16, v61
	v_mul_f32_e32 v14, v14, v15
	v_mul_f32_e32 v62, v96, v62
	v_mul_f32_e32 v14, v14, v61
	ds_read_u16 v61, v113 offset:6
	v_mul_f32_e32 v15, 0x3fb8aa3b, v62
	v_exp_f32_e32 v15, v15
	ds_write2st64_b32 v136, v60, v14 offset0:136 offset1:169
	v_add_f32_e32 v14, v62, v62
	v_cmp_nlt_f32_e64 s[52:53], s29, v14
	s_and_saveexec_b64 s[4:5], s[52:53]
	s_xor_b64 s[4:5], exec, s[4:5]
	v_fma_f32 v60, -v15, v15, 1.0
	s_andn2_saveexec_b64 s[4:5], s[4:5]
	v_pk_mul_f32 v[64:65], v[14:15], s[88:89] op_sel_hi:[0,1]
	v_add_f32_e32 v60, 1.0, v65
	v_fma_f32 v60, v64, v60, 1.0
	v_mul_f32_e64 v60, v60, -v14
	s_or_b64 exec, exec, s[4:5]
	v_add_f32_e32 v14, v11, v63
	v_mul_f32_e32 v14, 0xbfb8aa3b, v14
	v_add_f32_e32 v56, v4, v56
	v_exp_f32_e32 v14, v14
	v_mul_f32_e32 v56, 0xbfb8aa3b, v56
	v_exp_f32_e32 v56, v56
	v_add_f32_e32 v14, 1.0, v14
	v_max_f32_e32 v60, 0, v60
	v_rcp_f32_e32 v14, v14
	v_sqrt_f32_e32 v60, v60
	v_add_f32_e32 v56, 1.0, v56
	v_rcp_f32_e64 v56, -v56
	s_waitcnt lgkmcnt(1)
	v_lshlrev_b32_e32 v61, 16, v61
	v_mul_f32_e32 v14, v14, v60
	v_mul_f32_e32 v14, v14, v61
	v_mul_f32_e32 v61, v97, v56
	ds_read_u16 v60, v113 offset:32
	v_mul_f32_e32 v56, 0x3fb8aa3b, v61
	v_exp_f32_e32 v56, v56
	ds_write2st64_b32 v139, v15, v14 offset0:136 offset1:169
	v_add_f32_e32 v14, v61, v61
	v_cmp_nlt_f32_e64 s[52:53], s29, v14
	s_and_saveexec_b64 s[4:5], s[52:53]
	s_xor_b64 s[4:5], exec, s[4:5]
	v_fma_f32 v15, -v56, v56, 1.0
	s_andn2_saveexec_b64 s[4:5], s[4:5]
	v_pk_mul_f32 v[62:63], v[14:15], s[88:89] op_sel_hi:[0,1]
	v_add_f32_e32 v15, 1.0, v63
	v_fma_f32 v15, v62, v15, 1.0
	v_mul_f32_e64 v15, v15, -v14
	s_or_b64 exec, exec, s[4:5]
	v_add_f32_e32 v14, v16, v52
	v_mul_f32_e32 v14, 0xbfb8aa3b, v14
	v_add_f32_e32 v52, v5, v57
	v_exp_f32_e32 v14, v14
	v_mul_f32_e32 v52, 0xbfb8aa3b, v52
	v_exp_f32_e32 v52, v52
	v_add_f32_e32 v14, 1.0, v14
	v_max_f32_e32 v15, 0, v15
	v_rcp_f32_e32 v14, v14
	v_sqrt_f32_e32 v15, v15
	v_add_f32_e32 v52, 1.0, v52
	s_waitcnt lgkmcnt(1)
	v_lshlrev_b32_e32 v57, 16, v60
	v_rcp_f32_e64 v60, -v52
	v_mul_f32_e32 v14, v14, v15
	v_mul_f32_e32 v14, v14, v57
	ds_read_u16 v52, v113 offset:34
	v_mul_f32_e32 v57, v98, v60
	v_mul_f32_e32 v15, 0x3fb8aa3b, v57
	v_exp_f32_e32 v15, v15
	ds_write2st64_b32 v141, v56, v14 offset0:136 offset1:169
	v_add_f32_e32 v14, v57, v57
	v_cmp_nlt_f32_e64 s[52:53], s29, v14
	s_and_saveexec_b64 s[4:5], s[52:53]
	s_xor_b64 s[4:5], exec, s[4:5]
	v_fma_f32 v56, -v15, v15, 1.0
	s_andn2_saveexec_b64 s[4:5], s[4:5]
	v_pk_mul_f32 v[56:57], v[14:15], s[88:89] op_sel_hi:[0,1]
	v_add_f32_e32 v57, 1.0, v57
	v_fma_f32 v56, v56, v57, 1.0
	v_mul_f32_e64 v56, v56, -v14
	s_or_b64 exec, exec, s[4:5]
	v_add_f32_e32 v14, v17, v53
	v_max_f32_e32 v53, v56, v56
	v_add_f32_e32 v56, v6, v58
	v_mul_f32_e32 v14, 0xbfb8aa3b, v14
	v_mul_f32_e32 v56, 0xbfb8aa3b, v56
	v_exp_f32_e32 v14, v14
	v_exp_f32_e32 v56, v56
	v_max_f32_e32 v53, 0, v53
	v_sqrt_f32_e32 v53, v53
	v_add_f32_e32 v14, 1.0, v14
	v_add_f32_e32 v56, 1.0, v56
	v_rcp_f32_e32 v14, v14
	v_rcp_f32_e64 v56, -v56
	s_waitcnt lgkmcnt(1)
	v_lshlrev_b32_e32 v52, 16, v52
	v_mul_f32_e32 v14, v14, v53
	v_mul_f32_e32 v56, v99, v56
	v_mul_f32_e32 v14, v14, v52
	ds_read_u16 v53, v113 offset:36
	v_mul_f32_e32 v52, 0x3fb8aa3b, v56
	v_exp_f32_e32 v52, v52
	ds_write2st64_b32 v142, v15, v14 offset0:136 offset1:169
	v_add_f32_e32 v14, v56, v56
	v_cmp_nlt_f32_e64 s[52:53], s29, v14
	s_and_saveexec_b64 s[4:5], s[52:53]
	s_xor_b64 s[4:5], exec, s[4:5]
	v_fma_f32 v15, -v52, v52, 1.0
	s_andn2_saveexec_b64 s[4:5], s[4:5]
	v_pk_mul_f32 v[56:57], v[14:15], s[88:89] op_sel_hi:[0,1]
	v_add_f32_e32 v15, 1.0, v57
	v_fma_f32 v15, v56, v15, 1.0
	v_mul_f32_e64 v15, v15, -v14
	s_or_b64 exec, exec, s[4:5]
	v_add_f32_e32 v14, v18, v54
	v_add_f32_e32 v54, v7, v59
	v_mul_f32_e32 v14, 0xbfb8aa3b, v14
	v_mul_f32_e32 v54, 0xbfb8aa3b, v54
	v_exp_f32_e32 v14, v14
	v_exp_f32_e32 v54, v54
	v_max_f32_e32 v15, 0, v15
	v_add_f32_e32 v14, 1.0, v14
	v_add_f32_e32 v54, 1.0, v54
	v_rcp_f32_e32 v14, v14
	v_sqrt_f32_e32 v15, v15
	v_rcp_f32_e64 v54, -v54
	s_waitcnt lgkmcnt(1)
	v_lshlrev_b32_e32 v53, 16, v53
	v_mul_f32_e32 v14, v14, v15
	v_mul_f32_e32 v54, v105, v54
	v_mul_f32_e32 v14, v14, v53
	ds_read_u16 v53, v113 offset:38
	v_mul_f32_e32 v15, 0x3fb8aa3b, v54
	v_exp_f32_e32 v15, v15
	ds_write2st64_b32 v144, v52, v14 offset0:136 offset1:169
	v_add_f32_e32 v14, v54, v54
	v_cmp_nlt_f32_e64 s[52:53], s29, v14
	s_and_saveexec_b64 s[4:5], s[52:53]
	s_xor_b64 s[4:5], exec, s[4:5]
	v_fma_f32 v52, -v15, v15, 1.0
	s_andn2_saveexec_b64 s[4:5], s[4:5]
	v_pk_mul_f32 v[56:57], v[14:15], s[88:89] op_sel_hi:[0,1]
	v_add_f32_e32 v52, 1.0, v57
	v_fma_f32 v52, v56, v52, 1.0
	v_mul_f32_e64 v52, v52, -v14
	s_or_b64 exec, exec, s[4:5]
	s_waitcnt lgkmcnt(1)
	v_lshlrev_b32_e32 v14, 16, v53
	v_add_f32_e32 v53, v19, v55
	v_mul_f32_e32 v53, 0xbfb8aa3b, v53
	v_exp_f32_e32 v53, v53
	v_max_f32_e32 v52, 0, v52
	v_sqrt_f32_e32 v52, v52
	v_add_f32_e32 v53, 1.0, v53
	v_rcp_f32_e32 v53, v53
	s_nop 0
	v_mul_f32_e32 v52, v53, v52
	v_mul_f32_e32 v14, v52, v14
	ds_write2st64_b32 v145, v15, v14 offset0:136 offset1:169
	s_waitcnt lgkmcnt(0)
	s_barrier
	ds_read2_b32 v[14:15], v137 offset1:33
	ds_read2_b32 v[52:53], v138 offset0:64 offset1:97
	s_waitcnt lgkmcnt(0)
	v_fma_f32 v52, 0, v14, v52
	v_fmac_f32_e32 v53, v52, v15
	v_mul_f32_e32 v52, v14, v15
	ds_read2_b32 v[14:15], v137 offset0:66 offset1:99
	ds_read2_b32 v[54:55], v138 offset0:130 offset1:163
	s_waitcnt lgkmcnt(0)
	v_fma_f32 v53, v53, v14, v54
	v_mul_f32_e32 v14, v52, v14
	v_fmac_f32_e32 v55, v53, v15
	v_mul_f32_e32 v54, v14, v15
	ds_read2_b32 v[14:15], v137 offset0:132 offset1:165
	ds_read2_b32 v[52:53], v138 offset0:196 offset1:229
	s_waitcnt lgkmcnt(0)
	v_fma_f32 v52, v55, v14, v52
	v_mul_f32_e32 v14, v54, v14
	v_fmac_f32_e32 v53, v52, v15
	v_mul_f32_e32 v52, v14, v15
	ds_read2_b32 v[14:15], v137 offset0:198 offset1:231
	ds_read2_b32 v[54:55], v140 offset0:6 offset1:39
	s_waitcnt lgkmcnt(0)
	v_fma_f32 v53, v53, v14, v54
	v_mul_f32_e32 v14, v52, v14
	v_fmac_f32_e32 v55, v53, v15
	v_mul_f32_e32 v14, v14, v15
	ds_write2st64_b32 v78, v14, v55 offset0:202 offset1:206
	s_waitcnt lgkmcnt(0)
	s_barrier
	ds_read_b32 v14, v115 offset:53760
	s_and_saveexec_b64 s[4:5], vcc
	s_cbranch_execz .LBB0_1557
	ds_read2st64_b32 v[52:53], v115 offset0:202 offset1:206
	s_waitcnt lgkmcnt(0)
	v_fmac_f32_e32 v53, v14, v52
	v_mov_b32_e32 v14, v53
	s_or_b64 exec, exec, s[4:5]
	s_and_saveexec_b64 s[4:5], s[38:39]
	s_cbranch_execnz .LBB0_1558
